# DOWN0 epilogue: residual x lines touched up front (dummy dword loads) so the serialized f32 load ladder hits L2
# baseline (speedup 1.0000x reference)
; DI unsigned cvtpk(float lo, float hi) { f32x2_t v = {lo, hi}; bf16x2_t b = __builtin_convertvector(v, bf16x2_t); return __builtin_bit_cast(unsigned, b); }
;     DI void operator()(const f32x4 (&acc)[2][2][4][2], const Unit& u, int wr, int wc, int fr, int fq) const {
;     ...
; #pragma unroll
;         for (int ai = 0; ai < 2; ++ai)
; #pragma unroll
;             for (int m = 0; m < 4; ++m) {
;                 const int row = row0 + ai * HALF + m * 16; float ss = 0.f;
; #pragma unroll
;                 for (int bj = 0; bj < 2; ++bj) {
;                     const size_t off = (size_t)row * DM + col0 + bj * HALF;
;                     const f32x4 b0 = *(const f32x4*)(base + off), b1 = *(const f32x4*)(base + off + 4);
;                     const f32x4 x0 = b0 + alpha * acc[ai][bj][m][0], x1 = b1 + alpha * acc[ai][bj][m][1];
;                     if (out) { *(f32x4*)(out + off) = x0; *(f32x4*)(out + off + 4) = x1; }
;                     if (xb) { u32x4 w; w.x = cvtpk(x0[0], x0[1]); w.y = cvtpk(x0[2], x0[3]); w.z = cvtpk(x1[0], x1[1]); w.w = cvtpk(x1[2], x1[3]); *(u32x4*)(xb + off) = w; }
;                     ss += (x0[0] * x0[0] + x0[1] * x0[1]) + (x0[2] * x0[2] + x0[3] * x0[3]) + (x1[0] * x1[0] + x1[1] * x1[1]) + (x1[2] * x1[2] + x1[3] * x1[3]);
.LBB0_554:
	s_waitcnt lgkmcnt(0)
	v_lshlrev_b64 v[132:133], 10, v[234:235]
	v_lshl_add_u64 v[132:133], v[132:133], 0, v[220:221]
	v_lshl_add_u64 v[132:133], v[132:133], 2, s[0:1]
	global_load_dword v142, v[132:133], off
	global_load_dword v142, v[132:133], off offset:512
	v_lshlrev_b64 v[132:133], 10, v[232:233]
	v_lshl_add_u64 v[132:133], v[132:133], 0, v[220:221]
	v_lshl_add_u64 v[132:133], v[132:133], 2, s[0:1]
	global_load_dword v142, v[132:133], off
	global_load_dword v142, v[132:133], off offset:512
	v_lshlrev_b64 v[132:133], 10, v[230:231]
	v_lshl_add_u64 v[132:133], v[132:133], 0, v[220:221]
	v_lshl_add_u64 v[132:133], v[132:133], 2, s[0:1]
	global_load_dword v142, v[132:133], off
	global_load_dword v142, v[132:133], off offset:512
	v_lshlrev_b64 v[132:133], 10, v[228:229]
	v_lshl_add_u64 v[132:133], v[132:133], 0, v[220:221]
	v_lshl_add_u64 v[132:133], v[132:133], 2, s[0:1]
	global_load_dword v142, v[132:133], off
	global_load_dword v142, v[132:133], off offset:512
	v_lshlrev_b64 v[132:133], 10, v[226:227]
	v_lshl_add_u64 v[132:133], v[132:133], 0, v[220:221]
	v_lshl_add_u64 v[132:133], v[132:133], 2, s[0:1]
	global_load_dword v142, v[132:133], off
	global_load_dword v142, v[132:133], off offset:512
	v_lshlrev_b64 v[132:133], 10, v[224:225]
	v_lshl_add_u64 v[132:133], v[132:133], 0, v[220:221]
	v_lshl_add_u64 v[132:133], v[132:133], 2, s[0:1]
	global_load_dword v142, v[132:133], off
	global_load_dword v142, v[132:133], off offset:512
	v_lshlrev_b64 v[132:133], 10, v[222:223]
	v_lshl_add_u64 v[132:133], v[132:133], 0, v[220:221]
	v_lshl_add_u64 v[132:133], v[132:133], 2, s[0:1]
	global_load_dword v142, v[132:133], off
	global_load_dword v142, v[132:133], off offset:512
	v_lshlrev_b64 v[132:133], 10, v[218:219]
	v_lshl_add_u64 v[132:133], v[132:133], 0, v[220:221]
	v_lshl_add_u64 v[132:133], v[132:133], 2, s[0:1]
	global_load_dword v142, v[132:133], off
	global_load_dword v142, v[132:133], off offset:512
	v_lshlrev_b64 v[130:131], 10, v[234:235]
	v_lshl_add_u64 v[132:133], v[130:131], 0, v[220:221]
	v_lshl_add_u64 v[130:131], v[132:133], 2, s[0:1]
	global_load_dwordx4 v[134:137], v[130:131], off offset:16
	global_load_dwordx4 v[138:141], v[130:131], off
	s_and_b64 vcc, exec, s[78:79]
	s_waitcnt vmcnt(0)
	v_pk_fma_f32 v[124:125], s[84:85], v[124:125], v[136:137]
	v_pk_fma_f32 v[128:129], s[84:85], v[128:129], v[140:141]
	v_pk_fma_f32 v[126:127], s[66:67], v[126:127], v[138:139]
	v_pk_fma_f32 v[122:123], s[66:67], v[122:123], v[134:135]
	v_lshl_add_u64 v[134:135], v[132:133], 2, s[40:41]
	s_cbranch_vccz .LBB0_556
	global_store_dwordx4 v[134:135], v[126:129], off
	global_store_dwordx4 v[134:135], v[122:125], off offset:16
